# nt hint: input-projection epilogue stores + FNet fold / DFT-matrix / weight-conversion stores beside the scans
# baseline (speedup 1.0000x reference)
.LBB0_1301:
	v_cndmask_b32_e64 v66, -1.0, 1.0, s[0:1]
	s_waitcnt vmcnt(0)
	v_lshlrev_b32_e32 v70, 16, v6
	v_and_b32_e32 v71, 0xffff0000, v6
	v_lshlrev_b32_e32 v82, 16, v14
	v_and_b32_e32 v83, 0xffff0000, v14
	v_pk_fma_f32 v[70:71], v[66:67], v[82:83], v[70:71] op_sel_hi:[0,1,1]
	v_add_u32_e32 v6, 0x1000, v81
	ds_write2_b32 v6, v70, v71 offset1:1
	v_lshlrev_b32_e32 v6, 16, v7
	v_and_b32_e32 v7, 0xffff0000, v7
	v_lshlrev_b32_e32 v14, 16, v15
	v_and_b32_e32 v15, 0xffff0000, v15
	v_pk_fma_f32 v[6:7], v[66:67], v[14:15], v[6:7] op_sel_hi:[0,1,1]
	v_add_u32_e32 v14, 0x1008, v81
	ds_write2_b32 v14, v6, v7 offset1:1
	v_lshlrev_b32_e32 v6, 16, v8
	v_and_b32_e32 v7, 0xffff0000, v8
	v_lshlrev_b32_e32 v14, 16, v16
	v_and_b32_e32 v15, 0xffff0000, v16
	v_pk_fma_f32 v[6:7], v[66:67], v[14:15], v[6:7] op_sel_hi:[0,1,1]
	v_add_u32_e32 v8, 0x1010, v81
	ds_write2_b32 v8, v6, v7 offset1:1
	v_lshlrev_b32_e32 v6, 16, v9
	v_and_b32_e32 v7, 0xffff0000, v9
	v_lshlrev_b32_e32 v8, 16, v17
	v_and_b32_e32 v9, 0xffff0000, v17
	v_pk_fma_f32 v[6:7], v[66:67], v[8:9], v[6:7] op_sel_hi:[0,1,1]
	v_add_u32_e32 v8, 0x1018, v81
	ds_write2_b32 v8, v6, v7 offset1:1
	v_lshlrev_b32_e32 v6, 16, v2
	v_and_b32_e32 v7, 0xffff0000, v2
	v_lshlrev_b32_e32 v8, 16, v22
	v_and_b32_e32 v9, 0xffff0000, v22
	v_pk_fma_f32 v[6:7], v[66:67], v[8:9], v[6:7] op_sel_hi:[0,1,1]
	v_add_u32_e32 v2, 0x1820, v81
	ds_write2_b32 v2, v6, v7 offset1:1
	v_lshlrev_b32_e32 v2, 16, v3
	v_and_b32_e32 v3, 0xffff0000, v3
	v_lshlrev_b32_e32 v6, 16, v23
	v_and_b32_e32 v7, 0xffff0000, v23
	v_pk_fma_f32 v[2:3], v[66:67], v[6:7], v[2:3] op_sel_hi:[0,1,1]
	v_add_u32_e32 v6, 0x1828, v81
	ds_write2_b32 v6, v2, v3 offset1:1
	v_lshlrev_b32_e32 v2, 16, v4
	v_and_b32_e32 v3, 0xffff0000, v4
	v_lshlrev_b32_e32 v6, 16, v24
	v_and_b32_e32 v7, 0xffff0000, v24
	v_pk_fma_f32 v[2:3], v[66:67], v[6:7], v[2:3] op_sel_hi:[0,1,1]
	v_add_u32_e32 v4, 0x1830, v81
	ds_write2_b32 v4, v2, v3 offset1:1
	v_lshlrev_b32_e32 v2, 16, v5
	v_and_b32_e32 v3, 0xffff0000, v5
	v_lshlrev_b32_e32 v4, 16, v25
	v_and_b32_e32 v5, 0xffff0000, v25
	v_pk_fma_f32 v[2:3], v[66:67], v[4:5], v[2:3] op_sel_hi:[0,1,1]
	v_add_u32_e32 v4, 0x1838, v81
	ds_write2_b32 v4, v2, v3 offset1:1
	v_lshlrev_b32_e32 v2, 16, v10
	v_and_b32_e32 v3, 0xffff0000, v10
	v_lshlrev_b32_e32 v4, 16, v30
	v_and_b32_e32 v5, 0xffff0000, v30
	v_pk_fma_f32 v[2:3], v[66:67], v[4:5], v[2:3] op_sel_hi:[0,1,1]
	v_add_u32_e32 v4, 0x2040, v81
	ds_write2_b32 v4, v2, v3 offset1:1
	v_lshlrev_b32_e32 v2, 16, v11
	v_and_b32_e32 v3, 0xffff0000, v11
	v_lshlrev_b32_e32 v4, 16, v31
	v_and_b32_e32 v5, 0xffff0000, v31
	v_pk_fma_f32 v[2:3], v[66:67], v[4:5], v[2:3] op_sel_hi:[0,1,1]
	v_add_u32_e32 v4, 0x2048, v81
	ds_write2_b32 v4, v2, v3 offset1:1
	v_lshlrev_b32_e32 v2, 16, v12
	v_and_b32_e32 v3, 0xffff0000, v12
	v_lshlrev_b32_e32 v4, 16, v32
	v_and_b32_e32 v5, 0xffff0000, v32
	v_pk_fma_f32 v[2:3], v[66:67], v[4:5], v[2:3] op_sel_hi:[0,1,1]
	v_add_u32_e32 v4, 0x2050, v81
	ds_write2_b32 v4, v2, v3 offset1:1
	v_lshlrev_b32_e32 v2, 16, v13
	v_and_b32_e32 v3, 0xffff0000, v13
	v_lshlrev_b32_e32 v4, 16, v33
	v_and_b32_e32 v5, 0xffff0000, v33
	v_pk_fma_f32 v[2:3], v[66:67], v[4:5], v[2:3] op_sel_hi:[0,1,1]
	v_add_u32_e32 v4, 0x2058, v81
	ds_write2_b32 v4, v2, v3 offset1:1
	v_lshlrev_b32_e32 v2, 16, v18
	v_and_b32_e32 v3, 0xffff0000, v18
	v_lshlrev_b32_e32 v4, 16, v38
	v_and_b32_e32 v5, 0xffff0000, v38
	v_pk_fma_f32 v[2:3], v[66:67], v[4:5], v[2:3] op_sel_hi:[0,1,1]
	v_add_u32_e32 v4, 0x2860, v81
	ds_write2_b32 v4, v2, v3 offset1:1
	v_lshlrev_b32_e32 v2, 16, v19
	v_and_b32_e32 v3, 0xffff0000, v19
	v_lshlrev_b32_e32 v4, 16, v39
	v_and_b32_e32 v5, 0xffff0000, v39
	v_pk_fma_f32 v[2:3], v[66:67], v[4:5], v[2:3] op_sel_hi:[0,1,1]
	v_add_u32_e32 v4, 0x2868, v81
	ds_write2_b32 v4, v2, v3 offset1:1
	v_lshlrev_b32_e32 v2, 16, v20
	v_and_b32_e32 v3, 0xffff0000, v20
	v_lshlrev_b32_e32 v4, 16, v40
	v_and_b32_e32 v5, 0xffff0000, v40
	v_pk_fma_f32 v[2:3], v[66:67], v[4:5], v[2:3] op_sel_hi:[0,1,1]
	v_add_u32_e32 v4, 0x2870, v81
	ds_write2_b32 v4, v2, v3 offset1:1
	v_lshlrev_b32_e32 v2, 16, v21
	v_and_b32_e32 v3, 0xffff0000, v21
	v_lshlrev_b32_e32 v4, 16, v41
	v_and_b32_e32 v5, 0xffff0000, v41
	v_pk_fma_f32 v[2:3], v[66:67], v[4:5], v[2:3] op_sel_hi:[0,1,1]
	v_add_u32_e32 v4, 0x2878, v81
	ds_write2_b32 v4, v2, v3 offset1:1
	v_lshlrev_b32_e32 v2, 16, v26
	v_and_b32_e32 v3, 0xffff0000, v26
	v_lshlrev_b32_e32 v4, 16, v46
	v_and_b32_e32 v5, 0xffff0000, v46
	v_pk_fma_f32 v[2:3], v[66:67], v[4:5], v[2:3] op_sel_hi:[0,1,1]
	v_add_u32_e32 v4, 0x3080, v81
	ds_write2_b32 v4, v2, v3 offset1:1
	v_lshlrev_b32_e32 v2, 16, v27
	v_and_b32_e32 v3, 0xffff0000, v27
	v_lshlrev_b32_e32 v4, 16, v47
	v_and_b32_e32 v5, 0xffff0000, v47
	v_pk_fma_f32 v[2:3], v[66:67], v[4:5], v[2:3] op_sel_hi:[0,1,1]
	v_add_u32_e32 v4, 0x3088, v81
	ds_write2_b32 v4, v2, v3 offset1:1
	v_lshlrev_b32_e32 v2, 16, v28
	v_and_b32_e32 v3, 0xffff0000, v28
	v_lshlrev_b32_e32 v4, 16, v48
	v_and_b32_e32 v5, 0xffff0000, v48
	v_pk_fma_f32 v[2:3], v[66:67], v[4:5], v[2:3] op_sel_hi:[0,1,1]
	v_add_u32_e32 v4, 0x3090, v81
	ds_write2_b32 v4, v2, v3 offset1:1
	v_lshlrev_b32_e32 v2, 16, v29
	v_and_b32_e32 v3, 0xffff0000, v29
	v_lshlrev_b32_e32 v4, 16, v49
	v_and_b32_e32 v5, 0xffff0000, v49
	v_pk_fma_f32 v[2:3], v[66:67], v[4:5], v[2:3] op_sel_hi:[0,1,1]
	v_add_u32_e32 v4, 0x3098, v81
	ds_write2_b32 v4, v2, v3 offset1:1
	v_lshlrev_b32_e32 v2, 16, v34
	v_and_b32_e32 v3, 0xffff0000, v34
	v_lshlrev_b32_e32 v4, 16, v54
	v_and_b32_e32 v5, 0xffff0000, v54
	v_pk_fma_f32 v[2:3], v[66:67], v[4:5], v[2:3] op_sel_hi:[0,1,1]
	v_add_u32_e32 v4, 0x38a0, v81
	ds_write2_b32 v4, v2, v3 offset1:1
	v_lshlrev_b32_e32 v2, 16, v35
	v_and_b32_e32 v3, 0xffff0000, v35
	v_lshlrev_b32_e32 v4, 16, v55
	v_and_b32_e32 v5, 0xffff0000, v55
	v_pk_fma_f32 v[2:3], v[66:67], v[4:5], v[2:3] op_sel_hi:[0,1,1]
	v_add_u32_e32 v4, 0x38a8, v81
	ds_write2_b32 v4, v2, v3 offset1:1
	v_lshlrev_b32_e32 v2, 16, v36
	v_and_b32_e32 v3, 0xffff0000, v36
	v_lshlrev_b32_e32 v4, 16, v56
	v_and_b32_e32 v5, 0xffff0000, v56
	v_pk_fma_f32 v[2:3], v[66:67], v[4:5], v[2:3] op_sel_hi:[0,1,1]
	v_add_u32_e32 v4, 0x38b0, v81
	ds_write2_b32 v4, v2, v3 offset1:1
	v_lshlrev_b32_e32 v2, 16, v37
	v_and_b32_e32 v3, 0xffff0000, v37
	v_lshlrev_b32_e32 v4, 16, v57
	v_and_b32_e32 v5, 0xffff0000, v57
	v_pk_fma_f32 v[2:3], v[66:67], v[4:5], v[2:3] op_sel_hi:[0,1,1]
	v_add_u32_e32 v4, 0x38b8, v81
	ds_write2_b32 v4, v2, v3 offset1:1
	v_lshlrev_b32_e32 v2, 16, v42
	v_and_b32_e32 v3, 0xffff0000, v42
	v_lshlrev_b32_e32 v4, 16, v58
	v_and_b32_e32 v5, 0xffff0000, v58
	v_pk_fma_f32 v[2:3], v[66:67], v[4:5], v[2:3] op_sel_hi:[0,1,1]
	v_add_u32_e32 v4, 0x40c0, v81
	ds_write2_b32 v4, v2, v3 offset1:1
	v_lshlrev_b32_e32 v2, 16, v43
	v_and_b32_e32 v3, 0xffff0000, v43
	v_lshlrev_b32_e32 v4, 16, v59
	v_and_b32_e32 v5, 0xffff0000, v59
	v_pk_fma_f32 v[2:3], v[66:67], v[4:5], v[2:3] op_sel_hi:[0,1,1]
	v_add_u32_e32 v4, 0x40c8, v81
	ds_write2_b32 v4, v2, v3 offset1:1
	v_lshlrev_b32_e32 v2, 16, v44
	v_and_b32_e32 v3, 0xffff0000, v44
	v_lshlrev_b32_e32 v4, 16, v60
	v_and_b32_e32 v5, 0xffff0000, v60
	v_pk_fma_f32 v[2:3], v[66:67], v[4:5], v[2:3] op_sel_hi:[0,1,1]
	v_add_u32_e32 v4, 0x40d0, v81
	ds_write2_b32 v4, v2, v3 offset1:1
	v_lshlrev_b32_e32 v2, 16, v45
	v_and_b32_e32 v3, 0xffff0000, v45
	v_lshlrev_b32_e32 v4, 16, v61
	v_and_b32_e32 v5, 0xffff0000, v61
	v_pk_fma_f32 v[2:3], v[66:67], v[4:5], v[2:3] op_sel_hi:[0,1,1]
	v_add_u32_e32 v4, 0x40d8, v81
	ds_write2_b32 v4, v2, v3 offset1:1
	v_lshlrev_b32_e32 v2, 16, v50
	v_and_b32_e32 v3, 0xffff0000, v50
	v_lshlrev_b32_e32 v4, 16, v62
	v_and_b32_e32 v5, 0xffff0000, v62
	v_pk_fma_f32 v[2:3], v[66:67], v[4:5], v[2:3] op_sel_hi:[0,1,1]
	v_add_u32_e32 v4, 0x48e0, v81
	ds_write2_b32 v4, v2, v3 offset1:1
	v_lshlrev_b32_e32 v2, 16, v51
	v_and_b32_e32 v3, 0xffff0000, v51
	v_lshlrev_b32_e32 v4, 16, v63
	v_and_b32_e32 v5, 0xffff0000, v63
	v_pk_fma_f32 v[2:3], v[66:67], v[4:5], v[2:3] op_sel_hi:[0,1,1]
	v_add_u32_e32 v4, 0x48e8, v81
	ds_write2_b32 v4, v2, v3 offset1:1
	v_lshlrev_b32_e32 v2, 16, v52
	v_and_b32_e32 v3, 0xffff0000, v52
	v_lshlrev_b32_e32 v4, 16, v64
	v_and_b32_e32 v5, 0xffff0000, v64
	v_pk_fma_f32 v[2:3], v[66:67], v[4:5], v[2:3] op_sel_hi:[0,1,1]
	v_add_u32_e32 v4, 0x48f0, v81
	ds_write2_b32 v4, v2, v3 offset1:1
	v_lshlrev_b32_e32 v2, 16, v53
	v_and_b32_e32 v3, 0xffff0000, v53
	v_lshlrev_b32_e32 v4, 16, v65
	v_and_b32_e32 v5, 0xffff0000, v65
	v_pk_fma_f32 v[2:3], v[66:67], v[4:5], v[2:3] op_sel_hi:[0,1,1]
	v_add_u32_e32 v4, 0x48f8, v81
	ds_write2_b32 v4, v2, v3 offset1:1
	s_waitcnt lgkmcnt(0)
	v_add_u32_e32 v18, 0x1000, v74
	v_add_u32_e32 v19, 0x1400, v74
	ds_read2_b32 v[2:3], v18 offset1:65
	ds_read2_b32 v[4:5], v18 offset0:130 offset1:195
	ds_read2_b32 v[6:7], v19 offset0:4 offset1:69
	ds_read2_b32 v[8:9], v19 offset0:134 offset1:199
	s_lshl_b32 s4, s6, 11
	s_and_b64 s[0:1], s[8:9], exec
	s_cselect_b32 s0, 0x400, 0
	s_waitcnt lgkmcnt(3)
	v_cvt_pk_bf16_f32 v2, v2, v3
	s_waitcnt lgkmcnt(2)
	v_cvt_pk_bf16_f32 v3, v4, v5
	s_waitcnt lgkmcnt(1)
	v_cvt_pk_bf16_f32 v4, v6, v7
	s_waitcnt lgkmcnt(0)
	v_cvt_pk_bf16_f32 v5, v8, v9
	ds_read2_b32 v[8:9], v18 offset0:8 offset1:73
	ds_read2_b32 v[12:13], v18 offset0:138 offset1:203
	ds_read2_b32 v[14:15], v19 offset0:12 offset1:77
	ds_read2_b32 v[16:17], v19 offset0:142 offset1:207
	s_or_b32 s0, s0, s4
	s_or_b32 s4, s29, s0
	s_lshl_b32 s6, s30, 1
	v_lshl_add_u64 v[10:11], v[68:69], 0, s[6:7]
	v_or_b32_e32 v6, s4, v1
	v_mad_u64_u32 v[6:7], s[0:1], v6, s28, v[10:11]
	global_store_dwordx4 v[6:7], v[2:5], off nt
	v_or_b32_e32 v6, s4, v75
	v_mad_u64_u32 v[6:7], s[0:1], v6, s28, v[10:11]
	s_waitcnt lgkmcnt(3)
	v_cvt_pk_bf16_f32 v2, v8, v9
	s_waitcnt lgkmcnt(2)
	v_cvt_pk_bf16_f32 v3, v12, v13
	s_waitcnt lgkmcnt(1)
	v_cvt_pk_bf16_f32 v4, v14, v15
	s_waitcnt lgkmcnt(0)
	v_cvt_pk_bf16_f32 v5, v16, v17
	ds_read2_b32 v[8:9], v18 offset0:16 offset1:81
	ds_read2_b32 v[12:13], v18 offset0:146 offset1:211
	ds_read2_b32 v[14:15], v19 offset0:20 offset1:85
	ds_read2_b32 v[16:17], v19 offset0:150 offset1:215
	global_store_dwordx4 v[6:7], v[2:5], off nt
	v_or_b32_e32 v6, s4, v76
	v_mad_u64_u32 v[6:7], s[0:1], v6, s28, v[10:11]
	s_waitcnt lgkmcnt(3)
	v_cvt_pk_bf16_f32 v2, v8, v9
	s_waitcnt lgkmcnt(2)
	v_cvt_pk_bf16_f32 v3, v12, v13
	s_waitcnt lgkmcnt(1)
	v_cvt_pk_bf16_f32 v4, v14, v15
	s_waitcnt lgkmcnt(0)
	v_cvt_pk_bf16_f32 v5, v16, v17
	ds_read2_b32 v[8:9], v18 offset0:24 offset1:89
	ds_read2_b32 v[12:13], v18 offset0:154 offset1:219
	ds_read2_b32 v[14:15], v19 offset0:28 offset1:93
	ds_read2_b32 v[16:17], v19 offset0:158 offset1:223
	global_store_dwordx4 v[6:7], v[2:5], off nt
	v_or_b32_e32 v6, s4, v77
	v_mad_u64_u32 v[6:7], s[0:1], v6, s28, v[10:11]
	s_waitcnt lgkmcnt(3)
	v_cvt_pk_bf16_f32 v2, v8, v9
	s_waitcnt lgkmcnt(2)
	v_cvt_pk_bf16_f32 v3, v12, v13
	s_waitcnt lgkmcnt(1)
	v_cvt_pk_bf16_f32 v4, v14, v15
	s_waitcnt lgkmcnt(0)
	v_cvt_pk_bf16_f32 v5, v16, v17
	ds_read2_b32 v[8:9], v18 offset0:32 offset1:97
	ds_read2_b32 v[12:13], v18 offset0:162 offset1:227
	ds_read2_b32 v[14:15], v19 offset0:36 offset1:101
	ds_read2_b32 v[16:17], v19 offset0:166 offset1:231
	global_store_dwordx4 v[6:7], v[2:5], off nt
	v_or_b32_e32 v6, s4, v78
	v_mad_u64_u32 v[6:7], s[0:1], v6, s28, v[10:11]
	s_waitcnt lgkmcnt(3)
	v_cvt_pk_bf16_f32 v2, v8, v9
	s_waitcnt lgkmcnt(2)
	v_cvt_pk_bf16_f32 v3, v12, v13
	s_waitcnt lgkmcnt(1)
	v_cvt_pk_bf16_f32 v4, v14, v15
	s_waitcnt lgkmcnt(0)
	v_cvt_pk_bf16_f32 v5, v16, v17
	ds_read2_b32 v[8:9], v18 offset0:40 offset1:105
	ds_read2_b32 v[12:13], v18 offset0:170 offset1:235
	ds_read2_b32 v[14:15], v19 offset0:44 offset1:109
	ds_read2_b32 v[16:17], v19 offset0:174 offset1:239
	global_store_dwordx4 v[6:7], v[2:5], off nt
	v_or_b32_e32 v6, s4, v79
	v_mad_u64_u32 v[6:7], s[0:1], v6, s28, v[10:11]
	s_waitcnt lgkmcnt(3)
	v_cvt_pk_bf16_f32 v2, v8, v9
	s_waitcnt lgkmcnt(2)
	v_cvt_pk_bf16_f32 v3, v12, v13
	s_waitcnt lgkmcnt(1)
	v_cvt_pk_bf16_f32 v4, v14, v15
	s_waitcnt lgkmcnt(0)
	v_cvt_pk_bf16_f32 v5, v16, v17
	ds_read2_b32 v[8:9], v18 offset0:48 offset1:113
	ds_read2_b32 v[12:13], v18 offset0:178 offset1:243
	ds_read2_b32 v[14:15], v19 offset0:52 offset1:117
	ds_read2_b32 v[16:17], v19 offset0:182 offset1:247
	global_store_dwordx4 v[6:7], v[2:5], off nt
	v_or_b32_e32 v6, s4, v80
	v_mad_u64_u32 v[6:7], s[0:1], v6, s28, v[10:11]
	s_waitcnt lgkmcnt(3)
	v_cvt_pk_bf16_f32 v2, v8, v9
	s_waitcnt lgkmcnt(2)
	v_cvt_pk_bf16_f32 v3, v12, v13
	s_waitcnt lgkmcnt(1)
	v_cvt_pk_bf16_f32 v4, v14, v15
	s_waitcnt lgkmcnt(0)
	v_cvt_pk_bf16_f32 v5, v16, v17
	ds_read2_b32 v[8:9], v18 offset0:56 offset1:121
	ds_read2_b32 v[12:13], v18 offset0:186 offset1:251
	ds_read2_b32 v[14:15], v19 offset0:60 offset1:125
	ds_read2_b32 v[16:17], v19 offset0:190 offset1:255
	global_store_dwordx4 v[6:7], v[2:5], off nt
	v_or_b32_e32 v6, s4, v73
	v_mad_u64_u32 v[6:7], s[0:1], v6, s28, v[10:11]
	s_waitcnt lgkmcnt(3)
	v_cvt_pk_bf16_f32 v2, v8, v9
	s_waitcnt lgkmcnt(2)
	v_cvt_pk_bf16_f32 v3, v12, v13
	s_waitcnt lgkmcnt(1)
	v_cvt_pk_bf16_f32 v4, v14, v15
	s_waitcnt lgkmcnt(0)
	v_cvt_pk_bf16_f32 v5, v16, v17
	global_store_dwordx4 v[6:7], v[2:5], off nt
	s_waitcnt lgkmcnt(0)
	s_add_i32 s0, s16, 0x200
	s_cmpk_lt_i32 s16, 0xe80
	s_mov_b32 s16, s0
	s_cbranch_scc0 .LBB0_1334

.LBB0_1340:
	v_cvt_pk_bf16_f32 v24, v23, v24
	v_add_u32_e32 v23, 0x200, v22
	s_add_i32 s28, s28, s27
	v_cmp_lt_u32_e32 vcc, 15, v22
	v_cvt_pk_bf16_f32 v25, v25, v26
	v_cvt_pk_bf16_f32 v26, v27, v28
	v_cvt_pk_bf16_f32 v27, v29, v32
	global_store_dwordx4 v[4:5], v[24:27], off nt
	v_lshl_add_u64 v[4:5], v[4:5], 0, s[6:7]
	v_add_u32_e32 v21, 0x1000, v21
	s_or_b64 s[12:13], vcc, s[12:13]
	v_mov_b32_e32 v22, v23
	s_andn2_b64 exec, exec, s[12:13]
	s_cbranch_execz .LBB0_1337

.LBB0_1375:
	s_waitcnt vmcnt(0)
	ds_write2_b32 v2, v47, v48 offset0:172 offset1:238
	s_waitcnt lgkmcnt(0)
	s_sub_i32 s4, 0, s1
	ds_read2_b32 v[6:7], v41 offset1:33
	s_add_i32 s4, s4, s9
	s_waitcnt lgkmcnt(0)
	v_cvt_pk_bf16_f32 v48, v6, v7
	ds_read2_b32 v[6:7], v41 offset0:66 offset1:99
	v_add_u32_e32 v54, s4, v40
	s_waitcnt lgkmcnt(0)
	v_cvt_pk_bf16_f32 v49, v6, v7
	ds_read2_b32 v[6:7], v41 offset0:132 offset1:165
	s_ashr_i32 s1, s0, 31
	v_ashrrev_i32_e32 v55, 31, v54
	s_waitcnt lgkmcnt(0)
	v_cvt_pk_bf16_f32 v50, v6, v7
	ds_read2_b32 v[6:7], v41 offset0:198 offset1:231
	v_lshl_add_u64 v[52:53], s[0:1], 1, v[4:5]
	v_lshlrev_b64 v[56:57], 13, v[54:55]
	s_waitcnt lgkmcnt(0)
	v_cvt_pk_bf16_f32 v51, v6, v7
	ds_read2_b32 v[6:7], v41 offset0:8 offset1:41
	v_lshl_add_u64 v[56:57], v[52:53], 0, v[56:57]
	global_store_dwordx4 v[56:57], v[48:51], off nt
	v_add_u32_e32 v56, 8, v54
	v_ashrrev_i32_e32 v57, 31, v56
	s_waitcnt lgkmcnt(0)
	v_cvt_pk_bf16_f32 v48, v6, v7
	ds_read2_b32 v[6:7], v41 offset0:74 offset1:107
	s_waitcnt lgkmcnt(0)
	v_cvt_pk_bf16_f32 v49, v6, v7
	ds_read2_b32 v[6:7], v41 offset0:140 offset1:173
	s_waitcnt lgkmcnt(0)
	v_cvt_pk_bf16_f32 v50, v6, v7
	ds_read2_b32 v[6:7], v41 offset0:206 offset1:239
	v_lshlrev_b64 v[56:57], 13, v[56:57]
	s_waitcnt lgkmcnt(0)
	v_cvt_pk_bf16_f32 v51, v6, v7
	ds_read2_b32 v[6:7], v41 offset0:16 offset1:49
	v_lshl_add_u64 v[56:57], v[52:53], 0, v[56:57]
	global_store_dwordx4 v[56:57], v[48:51], off nt
	v_add_u32_e32 v56, 16, v54
	v_ashrrev_i32_e32 v57, 31, v56
	s_waitcnt lgkmcnt(0)
	v_cvt_pk_bf16_f32 v48, v6, v7
	ds_read2_b32 v[6:7], v41 offset0:82 offset1:115
	s_waitcnt lgkmcnt(0)
	v_cvt_pk_bf16_f32 v49, v6, v7
	ds_read2_b32 v[6:7], v41 offset0:148 offset1:181
	s_waitcnt lgkmcnt(0)
	v_cvt_pk_bf16_f32 v50, v6, v7
	ds_read2_b32 v[6:7], v41 offset0:214 offset1:247
	v_lshlrev_b64 v[56:57], 13, v[56:57]
	v_add_u32_e32 v54, 24, v54
	s_waitcnt lgkmcnt(0)
	v_cvt_pk_bf16_f32 v51, v6, v7
	ds_read2_b32 v[6:7], v41 offset0:24 offset1:57
	v_lshl_add_u64 v[56:57], v[52:53], 0, v[56:57]
	v_ashrrev_i32_e32 v55, 31, v54
	global_store_dwordx4 v[56:57], v[48:51], off nt
	v_lshlrev_b64 v[54:55], 13, v[54:55]
	v_lshl_add_u64 v[52:53], v[52:53], 0, v[54:55]
	s_waitcnt lgkmcnt(0)
	v_cvt_pk_bf16_f32 v48, v6, v7
	ds_read2_b32 v[6:7], v41 offset0:90 offset1:123
	s_waitcnt lgkmcnt(0)
	v_cvt_pk_bf16_f32 v49, v6, v7
	ds_read2_b32 v[6:7], v41 offset0:156 offset1:189
	s_waitcnt lgkmcnt(0)
	v_cvt_pk_bf16_f32 v50, v6, v7
	ds_read2_b32 v[6:7], v41 offset0:222 offset1:255
	s_waitcnt lgkmcnt(0)
	v_cvt_pk_bf16_f32 v51, v6, v7
	global_store_dwordx4 v[52:53], v[48:51], off nt
	s_waitcnt lgkmcnt(0)
	s_add_i32 s0, s8, 0x200
	v_add_u32_e32 v40, 0x4000, v40
	v_add_u32_e32 v1, 0x4000, v1
	s_cmpk_lt_i32 s8, 0x1e00
	s_mov_b32 s8, s0
	s_cbranch_scc0 .LBB0_1408
